# stack1 + P4 y_ret epilogue batch pipelining (loads a batch ahead, counted waits)
# speedup vs baseline: 1.0176x; 1.0176x over previous
.LBB0_696:
	v_lshlrev_b32_e32 v250, 1, v150
	v_lshl_add_u32 v250, v146, 12, v250
	s_lshl_b32 s98, s78, 3
	s_and_b32 s98, s98, -16
	s_lshl_b32 s98, s98, 2
	v_lshl_add_u32 v251, v148, 4, s98
	v_lshl_add_u32 v251, v146, 8, v251
	s_lshl_b32 s4, s78, 3
	s_and_b32 s4, s4, -16
	s_ashr_i32 s5, s4, 31
	s_lshl_b64 s[4:5], s[4:5], 2
	s_add_u32 s4, s60, s4
	s_addc_u32 s5, s61, s5
	v_ashrrev_i32_e32 v149, 31, v148
	v_lshl_add_u64 v[150:151], v[150:151], 1, s[0:1]
	v_lshlrev_b64 v[130:131], 12, v[146:147]
	v_lshl_add_u64 v[154:155], v[150:151], 0, v[130:131]
	v_lshl_add_u64 v[152:153], v[148:149], 4, s[4:5]
	v_lshlrev_b64 v[130:131], 8, v[146:147]
	v_lshl_add_u64 v[130:131], v[152:153], 0, v[130:131]
	global_load_dwordx4 v[164:167], v[154:155], off
	global_load_dwordx4 v[168:171], v[130:131], off
	v_add_u32_e32 v130, 16, v146
	v_ashrrev_i32_e32 v131, 31, v130
	v_lshlrev_b64 v[132:133], 8, v[130:131]
	v_lshl_add_u64 v[132:133], v[152:153], 0, v[132:133]
	global_load_dwordx4 v[172:175], v[132:133], off
	global_load_dwordx4 v[176:179], v[154:155], off offset:256
	v_mul_f32_e32 v132, 0xbfb8aa3b, v126
	v_mul_f32_e32 v135, 0xbfb8aa3b, v127
	v_mul_f32_e32 v133, 0xbfb8aa3b, v122
	v_mul_f32_e32 v156, 0xbfb8aa3b, v129
	v_mul_f32_e32 v157, 0xbfb8aa3b, v125
	v_exp_f32_e32 v163, v132
	v_exp_f32_e32 v135, v135
	v_lshlrev_b64 v[130:131], 12, v[130:131]
	v_exp_f32_e32 v184, v133
	v_exp_f32_e32 v185, v156
	v_exp_f32_e32 v186, v157
	v_lshl_add_u64 v[156:157], v[150:151], 0, v[130:131]
	global_load_dwordx4 v[180:183], v[156:157], off
	global_load_dwordx4 v[130:133], v[156:157], off offset:256
	v_add_u32_e32 v252, 0x20000, v250
	global_load_dwordx4 v[234:237], v252, s[0:1] offset:256
	global_load_dwordx4 v[238:241], v252, s[0:1]
	v_add_u32_e32 v253, 0x30000, v250
	global_load_dwordx4 v[242:245], v253, s[0:1] offset:256
	global_load_dwordx4 v[246:249], v253, s[0:1]
	v_add_u32_e32 v252, 0x3000, v251
	global_load_dwordx4 v[226:229], v252, s[60:61]
	v_add_u32_e32 v253, 0x2000, v251
	global_load_dwordx4 v[230:233], v253, s[60:61]
	v_add_f32_e32 v163, 1.0, v163
	v_add_f32_e32 v135, 1.0, v135
	v_add_f32_e32 v187, 1.0, v184
	v_add_f32_e32 v189, 1.0, v185
	v_rcp_f32_e32 v184, v163
	v_rcp_f32_e32 v185, v135
	v_mul_f32_e32 v137, 0xbfb8aa3b, v123
	v_mul_f32_e32 v147, 0xbfb8aa3b, v124
	v_exp_f32_e32 v137, v137
	v_pk_mul_f32 v[184:185], v[126:127], v[184:185]
	v_exp_f32_e32 v147, v147
	v_mov_b64_e32 v[148:149], s[38:39]
	v_mul_f32_e32 v139, 0xbfb8aa3b, v128
	v_exp_f32_e32 v139, v139
	v_add_f32_e32 v137, 1.0, v137
	v_add_f32_e32 v147, 1.0, v147
	v_add_f32_e32 v191, 1.0, v186
	v_rcp_f32_e32 v186, v187
	v_rcp_f32_e32 v187, v137
	v_rcp_f32_e32 v190, v147
	v_rcp_f32_e32 v191, v191
	v_add_f32_e32 v139, 1.0, v139
	v_rcp_f32_e32 v188, v139
	v_rcp_f32_e32 v189, v189
	v_pk_mul_f32 v[124:125], v[124:125], v[190:191]
	v_pk_mul_f32 v[122:123], v[122:123], v[186:187]
	v_pk_mul_f32 v[128:129], v[128:129], v[188:189]
	s_waitcnt vmcnt(6)
	v_lshlrev_b32_e32 v192, 16, v166
	v_mov_b32_e32 v126, v169
	v_mov_b32_e32 v127, v170
	v_mov_b32_e32 v169, v171
	v_pk_add_f32 v[126:127], v[126:127], v[168:169]
	v_and_b32_e32 v193, 0xffff0000, v166
	v_mov_b32_e32 v170, v173
	v_mov_b32_e32 v171, v174
	v_mov_b32_e32 v173, v175
	v_pk_add_f32 v[168:169], v[170:171], v[172:173]
	v_pk_add_f32 v[126:127], v[126:127], v[126:127] op_sel:[0,1] op_sel_hi:[1,0]
	v_pk_add_f32 v[168:169], v[168:169], v[168:169] op_sel:[0,1] op_sel_hi:[1,0]
	v_mov_b32_e32 v127, v126
	v_mov_b32_e32 v135, v168
	s_nop 0
	v_permlane16_swap_b32_e32 v126, v127
	v_permlane16_swap_b32_e32 v168, v135
	v_add_f32_e32 v127, v126, v127
	v_add_f32_e32 v126, v168, v135
	v_mov_b32_e32 v169, v127
	v_mov_b32_e32 v168, v126
	s_nop 0
	v_permlane32_swap_b32_e32 v127, v169
	v_permlane32_swap_b32_e32 v126, v168
	v_pk_add_f32 v[126:127], v[126:127], v[168:169]
	v_lshlrev_b32_e32 v166, 16, v167
	v_pk_fma_f32 v[126:127], v[126:127], s[36:37], v[148:149] op_sel_hi:[1,0,0]
	v_and_b32_e32 v167, 0xffff0000, v167
	v_mul_f32_e32 v135, 0x4b800000, v127
	v_cmp_gt_f32_e32 vcc, s76, v127
	v_pk_mul_f32 v[122:123], v[122:123], v[192:193]
	v_pk_mul_f32 v[124:125], v[124:125], v[166:167]
	v_cndmask_b32_e32 v127, v127, v135, vcc
	v_rsq_f32_e32 v127, v127
	v_lshlrev_b32_e32 v188, 16, v164
	v_and_b32_e32 v189, 0xffff0000, v164
	v_lshlrev_b32_e32 v164, 16, v165
	v_mul_f32_e32 v135, 0x45800000, v127
	v_cndmask_b32_e32 v168, v127, v135, vcc
	v_and_b32_e32 v165, 0xffff0000, v165
	v_pk_mul_f32 v[166:167], v[124:125], v[168:169] op_sel_hi:[1,0]
	v_pk_mul_f32 v[124:125], v[122:123], v[168:169] op_sel_hi:[1,0]
	v_pk_mul_f32 v[128:129], v[128:129], v[164:165]
	v_cvt_pk_bf16_f32 v124, v124, v125
	v_mul_f32_e32 v125, 0xbfb8aa3b, v118
	v_pk_mul_f32 v[128:129], v[128:129], v[168:169] op_sel_hi:[1,0]
	v_exp_f32_e32 v127, v125
	v_mul_f32_e32 v125, 0xbfb8aa3b, v114
	v_cvt_pk_bf16_f32 v123, v128, v129
	v_exp_f32_e32 v129, v125
	v_add_f32_e32 v127, 1.0, v127
	v_mul_f32_e32 v137, 0x4b800000, v126
	v_cmp_gt_f32_e64 s[4:5], s76, v126
	v_rcp_f32_e32 v128, v127
	v_add_f32_e32 v127, 1.0, v129
	v_mul_f32_e32 v129, 0xbfb8aa3b, v119
	v_cndmask_b32_e64 v126, v126, v137, s[4:5]
	v_exp_f32_e32 v129, v129
	v_mul_f32_e32 v135, 0xbfb8aa3b, v115
	v_rsq_f32_e32 v126, v126
	v_exp_f32_e32 v135, v135
	v_pk_mul_f32 v[170:171], v[184:185], v[188:189]
	v_cvt_pk_bf16_f32 v125, v166, v167
	v_pk_mul_f32 v[164:165], v[170:171], v[168:169] op_sel_hi:[1,0]
	v_mul_f32_e32 v137, 0x45800000, v126
	v_cvt_pk_bf16_f32 v122, v164, v165
	v_rcp_f32_e32 v164, v127
	v_add_f32_e32 v127, 1.0, v129
	v_rcp_f32_e32 v129, v127
	v_add_f32_e32 v127, 1.0, v135
	v_mul_f32_e32 v135, 0xbfb8aa3b, v120
	v_cndmask_b32_e64 v126, v126, v137, s[4:5]
	v_exp_f32_e32 v135, v135
	v_mul_f32_e32 v137, 0xbfb8aa3b, v116
	v_exp_f32_e32 v137, v137
	v_rcp_f32_e32 v165, v127
	v_add_f32_e32 v127, 1.0, v135
	v_mul_f32_e32 v135, 0xbfb8aa3b, v121
	v_rcp_f32_e32 v166, v127
	v_add_f32_e32 v127, 1.0, v137
	v_exp_f32_e32 v135, v135
	v_mul_f32_e32 v137, 0xbfb8aa3b, v117
	v_exp_f32_e32 v137, v137
	v_rcp_f32_e32 v170, v127
	v_add_f32_e32 v127, 1.0, v135
	v_rcp_f32_e32 v167, v127
	v_add_f32_e32 v127, 1.0, v137
	v_rcp_f32_e32 v171, v127
	v_lshlrev_b32_e32 v172, 16, v176
	v_and_b32_e32 v173, 0xffff0000, v176
	v_lshlrev_b32_e32 v174, 16, v177
	v_and_b32_e32 v175, 0xffff0000, v177
	v_lshlrev_b32_e32 v176, 16, v178
	v_and_b32_e32 v177, 0xffff0000, v178
	v_lshlrev_b32_e32 v178, 16, v179
	v_and_b32_e32 v179, 0xffff0000, v179
	v_pk_mul_f32 v[116:117], v[116:117], v[170:171]
	v_pk_mul_f32 v[114:115], v[114:115], v[164:165]
	v_pk_mul_f32 v[118:119], v[118:119], v[128:129]
	v_pk_mul_f32 v[114:115], v[114:115], v[176:177]
	v_pk_mul_f32 v[116:117], v[116:117], v[178:179]
	v_pk_mul_f32 v[120:121], v[120:121], v[166:167]
	v_pk_mul_f32 v[118:119], v[118:119], v[172:173]
	v_pk_mul_f32 v[128:129], v[116:117], v[168:169] op_sel_hi:[1,0]
	v_pk_mul_f32 v[116:117], v[114:115], v[168:169] op_sel_hi:[1,0]
	v_pk_mul_f32 v[120:121], v[120:121], v[174:175]
	v_pk_mul_f32 v[118:119], v[118:119], v[168:169] op_sel_hi:[1,0]
	v_cvt_pk_bf16_f32 v116, v116, v117
	v_mul_f32_e32 v117, 0xbfb8aa3b, v110
	v_pk_mul_f32 v[120:121], v[120:121], v[168:169] op_sel_hi:[1,0]
	v_cvt_pk_bf16_f32 v114, v118, v119
	v_exp_f32_e32 v118, v117
	v_mul_f32_e32 v117, 0xbfb8aa3b, v106
	v_cvt_pk_bf16_f32 v115, v120, v121
	v_exp_f32_e32 v119, v117
	v_mul_f32_e32 v120, 0xbfb8aa3b, v111
	v_mul_f32_e32 v121, 0xbfb8aa3b, v107
	v_exp_f32_e32 v120, v120
	v_exp_f32_e32 v121, v121
	v_add_f32_e32 v119, 1.0, v119
	v_cvt_pk_bf16_f32 v117, v128, v129
	v_rcp_f32_e32 v128, v119
	v_add_f32_e32 v119, 1.0, v120
	v_add_f32_e32 v120, 1.0, v121
	v_mul_f32_e32 v121, 0xbfb8aa3b, v112
	v_mul_f32_e32 v127, 0xbfb8aa3b, v108
	v_exp_f32_e32 v121, v121
	v_exp_f32_e32 v127, v127
	v_rcp_f32_e32 v129, v120
	v_add_f32_e32 v118, 1.0, v118
	v_add_f32_e32 v120, 1.0, v121
	v_add_f32_e32 v121, 1.0, v127
	v_mul_f32_e32 v127, 0xbfb8aa3b, v113
	v_exp_f32_e32 v127, v127
	v_rcp_f32_e32 v164, v121
	v_rcp_f32_e32 v118, v118
	v_rcp_f32_e32 v119, v119
	v_add_f32_e32 v121, 1.0, v127
	v_rcp_f32_e32 v120, v120
	v_rcp_f32_e32 v121, v121
	v_add_u32_e32 v174, 48, v146
	v_add_u32_e32 v176, 32, v146
	v_lshlrev_b32_e32 v166, 16, v180
	v_and_b32_e32 v167, 0xffff0000, v180
	v_lshlrev_b32_e32 v168, 16, v181
	v_and_b32_e32 v169, 0xffff0000, v181
	v_pk_mul_f32 v[112:113], v[112:113], v[120:121]
	v_pk_mul_f32 v[110:111], v[110:111], v[118:119]
	v_ashrrev_i32_e32 v175, 31, v174
	v_ashrrev_i32_e32 v177, 31, v176
	v_pk_mul_f32 v[166:167], v[110:111], v[166:167]
	v_pk_mul_f32 v[168:169], v[112:113], v[168:169]
	v_lshlrev_b64 v[110:111], 8, v[174:175]
	v_lshlrev_b64 v[112:113], 8, v[176:177]
	v_lshl_add_u64 v[110:111], v[152:153], 0, v[110:111]
	v_lshl_add_u64 v[118:119], v[152:153], 0, v[112:113]
	s_nop 0
	v_mul_f32_e32 v135, 0xbfb8aa3b, v109
	v_exp_f32_e32 v135, v135
	v_lshlrev_b32_e32 v170, 16, v182
	v_and_b32_e32 v171, 0xffff0000, v182
	v_lshlrev_b32_e32 v172, 16, v183
	v_add_f32_e32 v127, 1.0, v135
	v_rcp_f32_e32 v165, v127
	v_and_b32_e32 v173, 0xffff0000, v183
	v_pk_mul_f32 v[106:107], v[106:107], v[128:129]
	v_pk_mul_f32 v[166:167], v[166:167], v[126:127] op_sel_hi:[1,0]
	v_pk_mul_f32 v[108:109], v[108:109], v[164:165]
	v_pk_mul_f32 v[106:107], v[106:107], v[170:171]
	v_pk_mul_f32 v[108:109], v[108:109], v[172:173]
	v_pk_mul_f32 v[106:107], v[106:107], v[126:127] op_sel_hi:[1,0]
	v_pk_mul_f32 v[108:109], v[108:109], v[126:127] op_sel_hi:[1,0]
	v_cvt_pk_bf16_f32 v164, v166, v167
	v_cvt_pk_bf16_f32 v166, v106, v107
	v_mul_f32_e32 v107, 0xbfb8aa3b, v98
	v_cvt_pk_bf16_f32 v167, v108, v109
	v_mul_f32_e32 v108, 0xbfb8aa3b, v103
	v_exp_f32_e32 v107, v107
	v_exp_f32_e32 v109, v108
	v_mul_f32_e32 v108, 0xbfb8aa3b, v99
	v_pk_mul_f32 v[168:169], v[168:169], v[126:127] op_sel_hi:[1,0]
	v_exp_f32_e32 v127, v108
	v_add_f32_e32 v107, 1.0, v107
	v_rcp_f32_e32 v108, v107
	v_add_f32_e32 v107, 1.0, v109
	v_add_f32_e32 v109, 1.0, v127
	v_mul_f32_e32 v127, 0xbfb8aa3b, v104
	v_exp_f32_e32 v127, v127
	v_mul_f32_e32 v128, 0xbfb8aa3b, v100
	v_exp_f32_e32 v129, v128
	v_mul_f32_e32 v106, 0xbfb8aa3b, v102
	v_add_f32_e32 v127, 1.0, v127
	v_rcp_f32_e32 v128, v127
	v_add_f32_e32 v127, 1.0, v129
	v_mul_f32_e32 v129, 0xbfb8aa3b, v105
	v_exp_f32_e32 v129, v129
	v_mul_f32_e32 v135, 0xbfb8aa3b, v101
	v_exp_f32_e32 v106, v106
	v_exp_f32_e32 v135, v135
	v_rcp_f32_e32 v109, v109
	v_cvt_pk_bf16_f32 v165, v168, v169
	v_rcp_f32_e32 v168, v127
	v_add_f32_e32 v127, 1.0, v129
	v_add_f32_e32 v106, 1.0, v106
	v_rcp_f32_e32 v129, v127
	v_add_f32_e32 v127, 1.0, v135
	v_rcp_f32_e32 v106, v106
	v_rcp_f32_e32 v107, v107
	v_rcp_f32_e32 v169, v127
	v_lshlrev_b32_e32 v172, 16, v132
	v_and_b32_e32 v173, 0xffff0000, v132
	v_pk_mul_f32 v[98:99], v[98:99], v[108:109]
	v_pk_mul_f32 v[104:105], v[104:105], v[128:129]
	v_pk_mul_f32 v[98:99], v[98:99], v[172:173]
	v_lshlrev_b32_e32 v170, 16, v130
	v_pk_mul_f32 v[98:99], v[98:99], v[126:127] op_sel_hi:[1,0]
	v_and_b32_e32 v171, 0xffff0000, v130
	v_cvt_pk_bf16_f32 v128, v98, v99
	v_lshlrev_b64 v[98:99], 12, v[176:177]
	v_lshlrev_b32_e32 v130, 16, v131
	v_and_b32_e32 v131, 0xffff0000, v131
	v_lshlrev_b32_e32 v132, 16, v133
	v_and_b32_e32 v133, 0xffff0000, v133
	v_pk_mul_f32 v[102:103], v[102:103], v[106:107]
	v_pk_mul_f32 v[100:101], v[100:101], v[168:169]
	v_lshl_add_u64 v[108:109], v[150:151], 0, v[98:99]
	v_pk_mul_f32 v[102:103], v[102:103], v[170:171]
	v_pk_mul_f32 v[104:105], v[104:105], v[130:131]
	v_pk_mul_f32 v[100:101], v[100:101], v[132:133]
	v_lshlrev_b64 v[98:99], 12, v[174:175]
	v_pk_mul_f32 v[104:105], v[104:105], v[126:127] op_sel_hi:[1,0]
	v_pk_mul_f32 v[102:103], v[102:103], v[126:127] op_sel_hi:[1,0]
	v_pk_mul_f32 v[100:101], v[100:101], v[126:127] op_sel_hi:[1,0]
	v_lshl_add_u64 v[106:107], v[150:151], 0, v[98:99]
	v_cvt_pk_bf16_f32 v126, v102, v103
	v_cvt_pk_bf16_f32 v127, v104, v105
	v_cvt_pk_bf16_f32 v129, v100, v101
	s_waitcnt vmcnt(0)
	v_mov_b32_e32 v110, v226
	v_mov_b32_e32 v111, v227
	v_mov_b32_e32 v112, v228
	v_mov_b32_e32 v113, v229
	v_mov_b32_e32 v118, v230
	v_mov_b32_e32 v119, v231
	v_mov_b32_e32 v120, v232
	v_mov_b32_e32 v121, v233
	v_mov_b32_e32 v130, v234
	v_mov_b32_e32 v131, v235
	v_mov_b32_e32 v132, v236
	v_mov_b32_e32 v133, v237
	v_mov_b32_e32 v168, v238
	v_mov_b32_e32 v169, v239
	v_mov_b32_e32 v170, v240
	v_mov_b32_e32 v171, v241
	v_mov_b32_e32 v98, v242
	v_mov_b32_e32 v99, v243
	v_mov_b32_e32 v100, v244
	v_mov_b32_e32 v101, v245
	v_mov_b32_e32 v102, v246
	v_mov_b32_e32 v103, v247
	v_mov_b32_e32 v104, v248
	v_mov_b32_e32 v105, v249
	v_add_u32_e32 v252, 0x80000, v250
	global_load_dwordx4 v[234:237], v252, s[0:1] offset:256
	global_load_dwordx4 v[238:241], v252, s[0:1]
	v_add_u32_e32 v253, 0x90000, v250
	global_load_dwordx4 v[242:245], v253, s[0:1] offset:256
	global_load_dwordx4 v[246:249], v253, s[0:1]
	v_add_u32_e32 v252, 0x9000, v251
	global_load_dwordx4 v[226:229], v252, s[60:61]
	v_add_u32_e32 v253, 0x8000, v251
	global_load_dwordx4 v[230:233], v253, s[60:61]
	s_nop 0
	global_store_dwordx4 v[154:155], v[122:125], off nt
	global_store_dwordx4 v[154:155], v[114:117], off offset:256 nt
	global_store_dwordx4 v[156:157], v[164:167], off nt
	global_store_dwordx4 v[156:157], v[126:129], off offset:256 nt
	s_waitcnt vmcnt(10)
	v_mov_b32_e32 v114, v119
	v_mov_b32_e32 v115, v120
	v_mov_b32_e32 v119, v121
	v_pk_add_f32 v[114:115], v[114:115], v[118:119]
	v_mov_b32_e32 v118, v111
	v_mov_b32_e32 v119, v112
	v_mov_b32_e32 v111, v113
	v_pk_add_f32 v[110:111], v[118:119], v[110:111]
	v_pk_add_f32 v[114:115], v[114:115], v[114:115] op_sel:[0,1] op_sel_hi:[1,0]
	v_pk_add_f32 v[110:111], v[110:111], v[110:111] op_sel:[0,1] op_sel_hi:[1,0]
	v_mov_b32_e32 v115, v114
	v_mov_b32_e32 v111, v110
	s_nop 0
	v_permlane16_swap_b32_e32 v114, v115
	v_permlane16_swap_b32_e32 v110, v111
	v_add_f32_e32 v115, v114, v115
	v_add_f32_e32 v114, v110, v111
	v_mov_b32_e32 v117, v115
	v_mov_b32_e32 v116, v114
	s_nop 0
	v_permlane32_swap_b32_e32 v115, v117
	v_permlane32_swap_b32_e32 v114, v116
	v_pk_add_f32 v[110:111], v[114:115], v[116:117]
	v_mul_f32_e32 v113, 0xbfb8aa3b, v94
	v_pk_fma_f32 v[110:111], v[110:111], s[36:37], v[148:149] op_sel_hi:[1,0,0]
	v_exp_f32_e32 v113, v113
	v_mul_f32_e32 v112, 0x4b800000, v111
	v_cmp_gt_f32_e32 vcc, s76, v111
	v_cmp_gt_f32_e64 s[4:5], s76, v110
	v_mul_f32_e32 v114, 0xbfb8aa3b, v90
	v_cndmask_b32_e32 v111, v111, v112, vcc
	v_mul_f32_e32 v112, 0x4b800000, v110
	v_rsq_f32_e32 v111, v111
	v_cndmask_b32_e64 v110, v110, v112, s[4:5]
	v_rsq_f32_e32 v110, v110
	v_exp_f32_e32 v115, v114
	v_mul_f32_e32 v112, 0x45800000, v111
	v_cndmask_b32_e32 v112, v111, v112, vcc
	v_mul_f32_e32 v111, 0x45800000, v110
	v_cndmask_b32_e64 v110, v110, v111, s[4:5]
	v_add_f32_e32 v111, 1.0, v113
	v_mul_f32_e32 v113, 0xbfb8aa3b, v95
	v_rcp_f32_e32 v114, v111
	v_add_f32_e32 v111, 1.0, v115
	v_exp_f32_e32 v113, v113
	v_mul_f32_e32 v115, 0xbfb8aa3b, v91
	v_exp_f32_e32 v117, v115
	v_rcp_f32_e32 v116, v111
	v_add_f32_e32 v111, 1.0, v113
	v_mul_f32_e32 v113, 0xbfb8aa3b, v96
	v_rcp_f32_e32 v115, v111
	v_add_f32_e32 v111, 1.0, v117
	v_exp_f32_e32 v113, v113
	v_mul_f32_e32 v117, 0xbfb8aa3b, v92
	v_exp_f32_e32 v119, v117
	v_rcp_f32_e32 v117, v111
	v_add_f32_e32 v111, 1.0, v113
	v_mul_f32_e32 v113, 0xbfb8aa3b, v97
	v_rcp_f32_e32 v118, v111
	v_add_f32_e32 v111, 1.0, v119
	v_exp_f32_e32 v113, v113
	v_mul_f32_e32 v119, 0xbfb8aa3b, v93
	v_exp_f32_e32 v121, v119
	v_rcp_f32_e32 v120, v111
	v_add_f32_e32 v111, 1.0, v113
	v_rcp_f32_e32 v119, v111
	v_add_f32_e32 v111, 1.0, v121
	v_rcp_f32_e32 v121, v111
	v_lshlrev_b32_e32 v126, 16, v170
	v_and_b32_e32 v127, 0xffff0000, v170
	v_lshlrev_b32_e32 v128, 16, v171
	v_and_b32_e32 v129, 0xffff0000, v171
	v_pk_mul_f32 v[92:93], v[92:93], v[120:121]
	v_pk_mul_f32 v[90:91], v[90:91], v[116:117]
	v_lshlrev_b32_e32 v122, 16, v168
	v_and_b32_e32 v123, 0xffff0000, v168
	v_lshlrev_b32_e32 v124, 16, v169
	v_and_b32_e32 v125, 0xffff0000, v169
	v_pk_mul_f32 v[96:97], v[96:97], v[118:119]
	v_pk_mul_f32 v[94:95], v[94:95], v[114:115]
	v_pk_mul_f32 v[90:91], v[90:91], v[126:127]
	v_pk_mul_f32 v[92:93], v[92:93], v[128:129]
	v_pk_mul_f32 v[94:95], v[94:95], v[122:123]
	v_pk_mul_f32 v[96:97], v[96:97], v[124:125]
	v_pk_mul_f32 v[114:115], v[92:93], v[112:113] op_sel_hi:[1,0]
	v_pk_mul_f32 v[92:93], v[90:91], v[112:113] op_sel_hi:[1,0]
	v_pk_mul_f32 v[96:97], v[96:97], v[112:113] op_sel_hi:[1,0]
	v_pk_mul_f32 v[94:95], v[94:95], v[112:113] op_sel_hi:[1,0]
	v_cvt_pk_bf16_f32 v92, v92, v93
	v_mul_f32_e32 v93, 0xbfb8aa3b, v86
	v_cvt_pk_bf16_f32 v90, v94, v95
	v_cvt_pk_bf16_f32 v91, v96, v97
	v_exp_f32_e32 v94, v93
	v_mul_f32_e32 v93, 0xbfb8aa3b, v82
	v_mul_f32_e32 v96, 0xbfb8aa3b, v87
	v_exp_f32_e32 v95, v93
	v_exp_f32_e32 v97, v96
	v_mul_f32_e32 v96, 0xbfb8aa3b, v83
	v_exp_f32_e32 v111, v96
	v_add_f32_e32 v95, 1.0, v95
	v_rcp_f32_e32 v96, v95
	v_add_f32_e32 v95, 1.0, v97
	v_add_f32_e32 v97, 1.0, v111
	v_mul_f32_e32 v111, 0xbfb8aa3b, v88
	v_exp_f32_e32 v111, v111
	v_mul_f32_e32 v113, 0xbfb8aa3b, v84
	v_exp_f32_e32 v113, v113
	v_cvt_pk_bf16_f32 v93, v114, v115
	v_add_f32_e32 v111, 1.0, v111
	v_rcp_f32_e32 v114, v111
	v_add_f32_e32 v111, 1.0, v113
	v_mul_f32_e32 v113, 0xbfb8aa3b, v89
	v_exp_f32_e32 v113, v113
	v_mul_f32_e32 v115, 0xbfb8aa3b, v85
	v_exp_f32_e32 v117, v115
	v_rcp_f32_e32 v116, v111
	v_add_f32_e32 v111, 1.0, v113
	v_rcp_f32_e32 v115, v111
	v_add_f32_e32 v111, 1.0, v117
	v_add_f32_e32 v94, 1.0, v94
	v_rcp_f32_e32 v97, v97
	v_rcp_f32_e32 v117, v111
	v_rcp_f32_e32 v94, v94
	v_rcp_f32_e32 v95, v95
	v_lshlrev_b32_e32 v122, 16, v132
	v_and_b32_e32 v123, 0xffff0000, v132
	v_lshlrev_b32_e32 v124, 16, v133
	v_and_b32_e32 v125, 0xffff0000, v133
	v_pk_mul_f32 v[84:85], v[84:85], v[116:117]
	v_pk_mul_f32 v[82:83], v[82:83], v[96:97]
	v_lshlrev_b32_e32 v118, 16, v130
	v_and_b32_e32 v119, 0xffff0000, v130
	v_pk_mul_f32 v[86:87], v[86:87], v[94:95]
	v_pk_mul_f32 v[82:83], v[82:83], v[122:123]
	v_pk_mul_f32 v[84:85], v[84:85], v[124:125]
	v_lshlrev_b32_e32 v120, 16, v131
	v_and_b32_e32 v121, 0xffff0000, v131
	v_pk_mul_f32 v[88:89], v[88:89], v[114:115]
	v_pk_mul_f32 v[86:87], v[86:87], v[118:119]
	v_pk_mul_f32 v[94:95], v[84:85], v[112:113] op_sel_hi:[1,0]
	v_pk_mul_f32 v[84:85], v[82:83], v[112:113] op_sel_hi:[1,0]
	v_pk_mul_f32 v[88:89], v[88:89], v[120:121]
	v_pk_mul_f32 v[86:87], v[86:87], v[112:113] op_sel_hi:[1,0]
	v_cvt_pk_bf16_f32 v84, v84, v85
	v_mul_f32_e32 v85, 0xbfb8aa3b, v78
	v_pk_mul_f32 v[88:89], v[88:89], v[112:113] op_sel_hi:[1,0]
	v_cvt_pk_bf16_f32 v82, v86, v87
	v_exp_f32_e32 v86, v85
	v_mul_f32_e32 v85, 0xbfb8aa3b, v74
	v_cvt_pk_bf16_f32 v83, v88, v89
	v_exp_f32_e32 v87, v85
	v_mul_f32_e32 v88, 0xbfb8aa3b, v79
	v_mul_f32_e32 v89, 0xbfb8aa3b, v75
	v_exp_f32_e32 v88, v88
	v_exp_f32_e32 v89, v89
	v_add_f32_e32 v87, 1.0, v87
	v_cvt_pk_bf16_f32 v85, v94, v95
	v_rcp_f32_e32 v94, v87
	v_add_f32_e32 v87, 1.0, v88
	v_add_f32_e32 v88, 1.0, v89
	v_mul_f32_e32 v89, 0xbfb8aa3b, v80
	v_mul_f32_e32 v95, 0xbfb8aa3b, v76
	v_exp_f32_e32 v89, v89
	v_exp_f32_e32 v96, v95
	v_rcp_f32_e32 v95, v88
	v_add_f32_e32 v86, 1.0, v86
	v_add_f32_e32 v88, 1.0, v89
	v_add_f32_e32 v89, 1.0, v96
	v_mul_f32_e32 v96, 0xbfb8aa3b, v81
	v_exp_f32_e32 v97, v96
	v_mul_f32_e32 v96, 0xbfb8aa3b, v77
	v_exp_f32_e32 v111, v96
	v_rcp_f32_e32 v96, v89
	v_add_f32_e32 v89, 1.0, v97
	v_rcp_f32_e32 v86, v86
	v_rcp_f32_e32 v87, v87
	v_rcp_f32_e32 v88, v88
	v_rcp_f32_e32 v89, v89
	v_add_u32_e32 v116, 0x90, v146
	v_add_u32_e32 v118, 0x80, v146
	v_lshlrev_b32_e32 v112, 16, v102
	v_and_b32_e32 v113, 0xffff0000, v102
	v_lshlrev_b32_e32 v102, 16, v103
	v_and_b32_e32 v103, 0xffff0000, v103
	v_pk_mul_f32 v[80:81], v[80:81], v[88:89]
	v_pk_mul_f32 v[78:79], v[78:79], v[86:87]
	v_ashrrev_i32_e32 v117, 31, v116
	v_ashrrev_i32_e32 v119, 31, v118
	v_pk_mul_f32 v[112:113], v[78:79], v[112:113]
	v_pk_mul_f32 v[102:103], v[80:81], v[102:103]
	v_lshlrev_b64 v[78:79], 8, v[116:117]
	v_lshlrev_b64 v[80:81], 8, v[118:119]
	v_lshl_add_u64 v[78:79], v[152:153], 0, v[78:79]
	v_lshl_add_u64 v[86:87], v[152:153], 0, v[80:81]
	s_nop 0
	v_add_f32_e32 v97, 1.0, v111
	v_rcp_f32_e32 v97, v97
	v_lshlrev_b32_e32 v114, 16, v104
	v_and_b32_e32 v115, 0xffff0000, v104
	v_lshlrev_b32_e32 v104, 16, v105
	v_and_b32_e32 v105, 0xffff0000, v105
	v_pk_mul_f32 v[76:77], v[76:77], v[96:97]
	v_pk_mul_f32 v[74:75], v[74:75], v[94:95]
	v_pk_mul_f32 v[76:77], v[76:77], v[104:105]
	v_pk_mul_f32 v[74:75], v[74:75], v[114:115]
	v_pk_mul_f32 v[76:77], v[76:77], v[110:111] op_sel_hi:[1,0]
	v_pk_mul_f32 v[74:75], v[74:75], v[110:111] op_sel_hi:[1,0]
	v_cvt_pk_bf16_f32 v97, v76, v77
	v_cvt_pk_bf16_f32 v96, v74, v75
	v_mul_f32_e32 v75, 0xbfb8aa3b, v66
	v_mul_f32_e32 v76, 0xbfb8aa3b, v71
	v_pk_mul_f32 v[102:103], v[102:103], v[110:111] op_sel_hi:[1,0]
	v_exp_f32_e32 v75, v75
	v_exp_f32_e32 v77, v76
	v_mul_f32_e32 v76, 0xbfb8aa3b, v67
	v_cvt_pk_bf16_f32 v95, v102, v103
	v_exp_f32_e32 v102, v76
	v_mul_f32_e32 v103, 0xbfb8aa3b, v68
	v_mul_f32_e32 v104, 0xbfb8aa3b, v73
	v_add_f32_e32 v75, 1.0, v75
	v_exp_f32_e32 v103, v103
	v_exp_f32_e32 v105, v104
	v_mul_f32_e32 v104, 0xbfb8aa3b, v69
	v_pk_mul_f32 v[112:113], v[112:113], v[110:111] op_sel_hi:[1,0]
	v_mul_f32_e32 v74, 0xbfb8aa3b, v70
	v_rcp_f32_e32 v76, v75
	v_add_f32_e32 v75, 1.0, v77
	v_add_f32_e32 v77, 1.0, v102
	v_mul_f32_e32 v102, 0xbfb8aa3b, v72
	v_exp_f32_e32 v111, v104
	v_exp_f32_e32 v74, v74
	v_exp_f32_e32 v102, v102
	v_rcp_f32_e32 v77, v77
	v_add_f32_e32 v103, 1.0, v103
	v_rcp_f32_e32 v104, v103
	v_add_f32_e32 v103, 1.0, v105
	v_add_f32_e32 v105, 1.0, v111
	v_add_f32_e32 v74, 1.0, v74
	v_add_f32_e32 v102, 1.0, v102
	v_rcp_f32_e32 v105, v105
	v_rcp_f32_e32 v74, v74
	v_rcp_f32_e32 v75, v75
	v_rcp_f32_e32 v102, v102
	v_rcp_f32_e32 v103, v103
	v_lshlrev_b32_e32 v114, 16, v100
	v_and_b32_e32 v115, 0xffff0000, v100
	v_pk_mul_f32 v[66:67], v[66:67], v[76:77]
	v_lshlrev_b32_e32 v100, 16, v101
	v_pk_mul_f32 v[66:67], v[66:67], v[114:115]
	v_and_b32_e32 v101, 0xffff0000, v101
	v_pk_mul_f32 v[68:69], v[68:69], v[104:105]
	v_pk_mul_f32 v[66:67], v[66:67], v[110:111] op_sel_hi:[1,0]
	v_cvt_pk_bf16_f32 v94, v112, v113
	v_lshlrev_b32_e32 v112, 16, v98
	v_and_b32_e32 v113, 0xffff0000, v98
	v_lshlrev_b32_e32 v98, 16, v99
	v_and_b32_e32 v99, 0xffff0000, v99
	v_pk_mul_f32 v[72:73], v[72:73], v[102:103]
	v_pk_mul_f32 v[70:71], v[70:71], v[74:75]
	v_pk_mul_f32 v[68:69], v[68:69], v[100:101]
	v_cvt_pk_bf16_f32 v100, v66, v67
	v_lshlrev_b64 v[66:67], 12, v[118:119]
	v_pk_mul_f32 v[70:71], v[70:71], v[112:113]
	v_pk_mul_f32 v[72:73], v[72:73], v[98:99]
	v_lshl_add_u64 v[74:75], v[150:151], 0, v[66:67]
	v_pk_mul_f32 v[72:73], v[72:73], v[110:111] op_sel_hi:[1,0]
	v_pk_mul_f32 v[70:71], v[70:71], v[110:111] op_sel_hi:[1,0]
	v_pk_mul_f32 v[68:69], v[68:69], v[110:111] op_sel_hi:[1,0]
	v_lshlrev_b64 v[66:67], 12, v[116:117]
	v_lshl_add_u64 v[76:77], v[150:151], 0, v[66:67]
	v_cvt_pk_bf16_f32 v98, v70, v71
	v_cvt_pk_bf16_f32 v99, v72, v73
	v_cvt_pk_bf16_f32 v101, v68, v69
	s_waitcnt vmcnt(4)
	v_mov_b32_e32 v78, v226
	v_mov_b32_e32 v79, v227
	v_mov_b32_e32 v80, v228
	v_mov_b32_e32 v81, v229
	v_mov_b32_e32 v86, v230
	v_mov_b32_e32 v87, v231
	v_mov_b32_e32 v88, v232
	v_mov_b32_e32 v89, v233
	v_mov_b32_e32 v102, v234
	v_mov_b32_e32 v103, v235
	v_mov_b32_e32 v104, v236
	v_mov_b32_e32 v105, v237
	v_mov_b32_e32 v110, v238
	v_mov_b32_e32 v111, v239
	v_mov_b32_e32 v112, v240
	v_mov_b32_e32 v113, v241
	v_mov_b32_e32 v66, v242
	v_mov_b32_e32 v67, v243
	v_mov_b32_e32 v68, v244
	v_mov_b32_e32 v69, v245
	v_mov_b32_e32 v70, v246
	v_mov_b32_e32 v71, v247
	v_mov_b32_e32 v72, v248
	v_mov_b32_e32 v73, v249
	v_add_u32_e32 v252, 0xa0000, v250
	global_load_dwordx4 v[234:237], v252, s[0:1] offset:256
	global_load_dwordx4 v[238:241], v252, s[0:1]
	v_add_u32_e32 v253, 0xb0000, v250
	global_load_dwordx4 v[242:245], v253, s[0:1] offset:256
	global_load_dwordx4 v[246:249], v253, s[0:1]
	v_add_u32_e32 v252, 0xb000, v251
	global_load_dwordx4 v[226:229], v252, s[60:61]
	v_add_u32_e32 v253, 0xa000, v251
	global_load_dwordx4 v[230:233], v253, s[60:61]
	s_nop 0
	global_store_dwordx4 v[108:109], v[90:93], off nt
	global_store_dwordx4 v[108:109], v[82:85], off offset:256 nt
	global_store_dwordx4 v[106:107], v[94:97], off nt
	global_store_dwordx4 v[106:107], v[98:101], off offset:256 nt
	s_waitcnt vmcnt(10)
	v_mov_b32_e32 v82, v87
	v_mov_b32_e32 v83, v88
	v_mov_b32_e32 v87, v89
	v_pk_add_f32 v[82:83], v[82:83], v[86:87]
	v_mov_b32_e32 v86, v79
	v_mov_b32_e32 v87, v80
	v_mov_b32_e32 v79, v81
	v_pk_add_f32 v[78:79], v[86:87], v[78:79]
	v_pk_add_f32 v[82:83], v[82:83], v[82:83] op_sel:[0,1] op_sel_hi:[1,0]
	v_pk_add_f32 v[78:79], v[78:79], v[78:79] op_sel:[0,1] op_sel_hi:[1,0]
	v_mov_b32_e32 v83, v82
	v_mov_b32_e32 v79, v78
	s_nop 0
	v_permlane16_swap_b32_e32 v82, v83
	v_permlane16_swap_b32_e32 v78, v79
	v_add_f32_e32 v83, v82, v83
	v_add_f32_e32 v82, v78, v79
	v_mov_b32_e32 v85, v83
	v_mov_b32_e32 v84, v82
	s_nop 0
	v_permlane32_swap_b32_e32 v83, v85
	v_permlane32_swap_b32_e32 v82, v84
	v_pk_add_f32 v[78:79], v[82:83], v[84:85]
	v_mul_f32_e32 v81, 0xbfb8aa3b, v62
	v_pk_fma_f32 v[78:79], v[78:79], s[36:37], v[148:149] op_sel_hi:[1,0,0]
	v_exp_f32_e32 v81, v81
	v_mul_f32_e32 v80, 0x4b800000, v79
	v_cmp_gt_f32_e32 vcc, s76, v79
	v_cmp_gt_f32_e64 s[4:5], s76, v78
	v_mul_f32_e32 v82, 0xbfb8aa3b, v58
	v_cndmask_b32_e32 v79, v79, v80, vcc
	v_mul_f32_e32 v80, 0x4b800000, v78
	v_rsq_f32_e32 v79, v79
	v_cndmask_b32_e64 v78, v78, v80, s[4:5]
	v_rsq_f32_e32 v78, v78
	v_exp_f32_e32 v83, v82
	v_mul_f32_e32 v80, 0x45800000, v79
	v_cndmask_b32_e32 v80, v79, v80, vcc
	v_mul_f32_e32 v79, 0x45800000, v78
	v_cndmask_b32_e64 v78, v78, v79, s[4:5]
	v_add_f32_e32 v79, 1.0, v81
	v_mul_f32_e32 v81, 0xbfb8aa3b, v63
	v_rcp_f32_e32 v82, v79
	v_add_f32_e32 v79, 1.0, v83
	v_exp_f32_e32 v81, v81
	v_mul_f32_e32 v83, 0xbfb8aa3b, v59
	v_exp_f32_e32 v85, v83
	v_rcp_f32_e32 v84, v79
	v_add_f32_e32 v79, 1.0, v81
	v_mul_f32_e32 v81, 0xbfb8aa3b, v64
	v_rcp_f32_e32 v83, v79
	v_add_f32_e32 v79, 1.0, v85
	v_exp_f32_e32 v81, v81
	v_mul_f32_e32 v85, 0xbfb8aa3b, v60
	v_exp_f32_e32 v87, v85
	v_rcp_f32_e32 v85, v79
	v_add_f32_e32 v79, 1.0, v81
	v_mul_f32_e32 v81, 0xbfb8aa3b, v65
	v_rcp_f32_e32 v86, v79
	v_add_f32_e32 v79, 1.0, v87
	v_exp_f32_e32 v81, v81
	v_mul_f32_e32 v87, 0xbfb8aa3b, v61
	v_exp_f32_e32 v89, v87
	v_rcp_f32_e32 v88, v79
	v_add_f32_e32 v79, 1.0, v81
	v_rcp_f32_e32 v87, v79
	v_add_f32_e32 v79, 1.0, v89
	v_rcp_f32_e32 v89, v79
	v_pk_mul_f32 v[58:59], v[58:59], v[84:85]
	v_lshlrev_b32_e32 v94, 16, v112
	v_and_b32_e32 v95, 0xffff0000, v112
	v_lshlrev_b32_e32 v96, 16, v113
	v_and_b32_e32 v97, 0xffff0000, v113
	v_pk_mul_f32 v[60:61], v[60:61], v[88:89]
	v_lshlrev_b32_e32 v90, 16, v110
	v_and_b32_e32 v91, 0xffff0000, v110
	v_lshlrev_b32_e32 v92, 16, v111
	v_and_b32_e32 v93, 0xffff0000, v111
	v_pk_mul_f32 v[64:65], v[64:65], v[86:87]
	v_pk_mul_f32 v[62:63], v[62:63], v[82:83]
	v_pk_mul_f32 v[58:59], v[58:59], v[94:95]
	v_pk_mul_f32 v[60:61], v[60:61], v[96:97]
	v_pk_mul_f32 v[62:63], v[62:63], v[90:91]
	v_pk_mul_f32 v[64:65], v[64:65], v[92:93]
	v_pk_mul_f32 v[82:83], v[60:61], v[80:81] op_sel_hi:[1,0]
	v_pk_mul_f32 v[60:61], v[58:59], v[80:81] op_sel_hi:[1,0]
	v_pk_mul_f32 v[64:65], v[64:65], v[80:81] op_sel_hi:[1,0]
	v_pk_mul_f32 v[62:63], v[62:63], v[80:81] op_sel_hi:[1,0]
	v_cvt_pk_bf16_f32 v60, v60, v61
	v_mul_f32_e32 v61, 0xbfb8aa3b, v54
	v_cvt_pk_bf16_f32 v58, v62, v63
	v_cvt_pk_bf16_f32 v59, v64, v65
	v_exp_f32_e32 v62, v61
	v_mul_f32_e32 v61, 0xbfb8aa3b, v50
	v_mul_f32_e32 v64, 0xbfb8aa3b, v55
	v_exp_f32_e32 v63, v61
	v_exp_f32_e32 v65, v64
	v_mul_f32_e32 v64, 0xbfb8aa3b, v51
	v_exp_f32_e32 v79, v64
	v_add_f32_e32 v63, 1.0, v63
	v_rcp_f32_e32 v64, v63
	v_add_f32_e32 v63, 1.0, v65
	v_add_f32_e32 v65, 1.0, v79
	v_mul_f32_e32 v79, 0xbfb8aa3b, v56
	v_exp_f32_e32 v79, v79
	v_mul_f32_e32 v81, 0xbfb8aa3b, v52
	v_exp_f32_e32 v81, v81
	v_cvt_pk_bf16_f32 v61, v82, v83
	v_add_f32_e32 v79, 1.0, v79
	v_rcp_f32_e32 v82, v79
	v_add_f32_e32 v79, 1.0, v81
	v_mul_f32_e32 v81, 0xbfb8aa3b, v57
	v_exp_f32_e32 v81, v81
	v_mul_f32_e32 v83, 0xbfb8aa3b, v53
	v_exp_f32_e32 v85, v83
	v_rcp_f32_e32 v84, v79
	v_add_f32_e32 v79, 1.0, v81
	v_rcp_f32_e32 v83, v79
	v_add_f32_e32 v79, 1.0, v85
	v_add_f32_e32 v62, 1.0, v62
	v_rcp_f32_e32 v65, v65
	v_rcp_f32_e32 v85, v79
	v_rcp_f32_e32 v62, v62
	v_rcp_f32_e32 v63, v63
	v_lshlrev_b32_e32 v90, 16, v104
	v_and_b32_e32 v91, 0xffff0000, v104
	v_lshlrev_b32_e32 v92, 16, v105
	v_and_b32_e32 v93, 0xffff0000, v105
	v_pk_mul_f32 v[52:53], v[52:53], v[84:85]
	v_pk_mul_f32 v[50:51], v[50:51], v[64:65]
	v_lshlrev_b32_e32 v86, 16, v102
	v_and_b32_e32 v87, 0xffff0000, v102
	v_pk_mul_f32 v[54:55], v[54:55], v[62:63]
	v_pk_mul_f32 v[50:51], v[50:51], v[90:91]
	v_pk_mul_f32 v[52:53], v[52:53], v[92:93]
	v_lshlrev_b32_e32 v88, 16, v103
	v_and_b32_e32 v89, 0xffff0000, v103
	v_pk_mul_f32 v[56:57], v[56:57], v[82:83]
	v_pk_mul_f32 v[54:55], v[54:55], v[86:87]
	v_pk_mul_f32 v[62:63], v[52:53], v[80:81] op_sel_hi:[1,0]
	v_pk_mul_f32 v[52:53], v[50:51], v[80:81] op_sel_hi:[1,0]
	v_pk_mul_f32 v[56:57], v[56:57], v[88:89]
	v_pk_mul_f32 v[54:55], v[54:55], v[80:81] op_sel_hi:[1,0]
	v_cvt_pk_bf16_f32 v52, v52, v53
	v_mul_f32_e32 v53, 0xbfb8aa3b, v46
	v_pk_mul_f32 v[56:57], v[56:57], v[80:81] op_sel_hi:[1,0]
	v_cvt_pk_bf16_f32 v50, v54, v55
	v_exp_f32_e32 v54, v53
	v_mul_f32_e32 v53, 0xbfb8aa3b, v42
	v_cvt_pk_bf16_f32 v51, v56, v57
	v_exp_f32_e32 v55, v53
	v_mul_f32_e32 v56, 0xbfb8aa3b, v47
	v_mul_f32_e32 v57, 0xbfb8aa3b, v43
	v_exp_f32_e32 v56, v56
	v_exp_f32_e32 v57, v57
	v_add_f32_e32 v55, 1.0, v55
	v_cvt_pk_bf16_f32 v53, v62, v63
	v_rcp_f32_e32 v62, v55
	v_add_f32_e32 v55, 1.0, v56
	v_add_f32_e32 v56, 1.0, v57
	v_mul_f32_e32 v57, 0xbfb8aa3b, v48
	v_mul_f32_e32 v63, 0xbfb8aa3b, v44
	v_exp_f32_e32 v57, v57
	v_exp_f32_e32 v64, v63
	v_rcp_f32_e32 v63, v56
	v_add_f32_e32 v54, 1.0, v54
	v_add_f32_e32 v56, 1.0, v57
	v_add_f32_e32 v57, 1.0, v64
	v_mul_f32_e32 v64, 0xbfb8aa3b, v49
	v_exp_f32_e32 v65, v64
	v_mul_f32_e32 v64, 0xbfb8aa3b, v45
	v_exp_f32_e32 v79, v64
	v_rcp_f32_e32 v64, v57
	v_add_f32_e32 v57, 1.0, v65
	v_rcp_f32_e32 v54, v54
	v_rcp_f32_e32 v55, v55
	v_rcp_f32_e32 v56, v56
	v_rcp_f32_e32 v57, v57
	v_lshlrev_b32_e32 v80, 16, v70
	v_and_b32_e32 v81, 0xffff0000, v70
	v_lshlrev_b32_e32 v70, 16, v71
	v_and_b32_e32 v71, 0xffff0000, v71
	v_pk_mul_f32 v[48:49], v[48:49], v[56:57]
	v_pk_mul_f32 v[46:47], v[46:47], v[54:55]
	v_add_u32_e32 v84, 0xb0, v146
	v_add_u32_e32 v86, 0xa0, v146
	v_pk_mul_f32 v[80:81], v[46:47], v[80:81]
	v_pk_mul_f32 v[46:47], v[48:49], v[70:71]
	v_ashrrev_i32_e32 v85, 31, v84
	v_ashrrev_i32_e32 v87, 31, v86
	v_pk_mul_f32 v[70:71], v[46:47], v[78:79] op_sel_hi:[1,0]
	v_lshlrev_b64 v[46:47], 8, v[84:85]
	v_lshlrev_b64 v[48:49], 8, v[86:87]
	v_lshl_add_u64 v[46:47], v[152:153], 0, v[46:47]
	v_lshl_add_u64 v[54:55], v[152:153], 0, v[48:49]
	s_nop 0
	v_add_f32_e32 v65, 1.0, v79
	v_rcp_f32_e32 v65, v65
	v_lshlrev_b32_e32 v82, 16, v72
	v_and_b32_e32 v83, 0xffff0000, v72
	v_lshlrev_b32_e32 v72, 16, v73
	v_and_b32_e32 v73, 0xffff0000, v73
	v_pk_mul_f32 v[44:45], v[44:45], v[64:65]
	v_pk_mul_f32 v[42:43], v[42:43], v[62:63]
	v_pk_mul_f32 v[44:45], v[44:45], v[72:73]
	v_pk_mul_f32 v[42:43], v[42:43], v[82:83]
	v_pk_mul_f32 v[44:45], v[44:45], v[78:79] op_sel_hi:[1,0]
	v_pk_mul_f32 v[42:43], v[42:43], v[78:79] op_sel_hi:[1,0]
	v_cvt_pk_bf16_f32 v65, v44, v45
	v_cvt_pk_bf16_f32 v64, v42, v43
	v_mul_f32_e32 v43, 0xbfb8aa3b, v34
	v_mul_f32_e32 v44, 0xbfb8aa3b, v39
	v_exp_f32_e32 v43, v43
	v_exp_f32_e32 v45, v44
	v_mul_f32_e32 v44, 0xbfb8aa3b, v35
	v_cvt_pk_bf16_f32 v63, v70, v71
	v_exp_f32_e32 v70, v44
	v_add_f32_e32 v43, 1.0, v43
	v_rcp_f32_e32 v44, v43
	v_add_f32_e32 v43, 1.0, v45
	v_add_f32_e32 v45, 1.0, v70
	v_mul_f32_e32 v70, 0xbfb8aa3b, v40
	v_exp_f32_e32 v70, v70
	v_mul_f32_e32 v71, 0xbfb8aa3b, v36
	v_exp_f32_e32 v71, v71
	v_pk_mul_f32 v[80:81], v[80:81], v[78:79] op_sel_hi:[1,0]
	v_add_f32_e32 v70, 1.0, v70
	v_cvt_pk_bf16_f32 v62, v80, v81
	v_rcp_f32_e32 v80, v70
	v_add_f32_e32 v70, 1.0, v71
	v_rcp_f32_e32 v82, v70
	v_mul_f32_e32 v70, 0xbfb8aa3b, v41
	v_exp_f32_e32 v79, v70
	v_mul_f32_e32 v70, 0xbfb8aa3b, v37
	v_exp_f32_e32 v83, v70
	v_lshlrev_b64 v[70:71], 12, v[84:85]
	v_lshl_add_u64 v[152:153], v[150:151], 0, v[70:71]
	v_mul_f32_e32 v42, 0xbfb8aa3b, v38
	v_exp_f32_e32 v42, v42
	v_add_f32_e32 v79, 1.0, v79
	v_rcp_f32_e32 v81, v79
	v_add_f32_e32 v79, 1.0, v83
	v_add_f32_e32 v42, 1.0, v42
	v_rcp_f32_e32 v42, v42
	v_rcp_f32_e32 v43, v43
	v_rcp_f32_e32 v45, v45
	v_rcp_f32_e32 v83, v79
	v_lshlrev_b32_e32 v84, 16, v66
	v_and_b32_e32 v85, 0xffff0000, v66
	v_lshlrev_b32_e32 v66, 16, v67
	v_and_b32_e32 v67, 0xffff0000, v67
	v_lshlrev_b32_e32 v88, 16, v68
	v_and_b32_e32 v89, 0xffff0000, v68
	v_lshlrev_b32_e32 v68, 16, v69
	v_and_b32_e32 v69, 0xffff0000, v69
	v_pk_mul_f32 v[40:41], v[40:41], v[80:81]
	v_pk_mul_f32 v[38:39], v[38:39], v[42:43]
	v_pk_mul_f32 v[36:37], v[36:37], v[82:83]
	v_pk_mul_f32 v[34:35], v[34:35], v[44:45]
	v_pk_mul_f32 v[38:39], v[38:39], v[84:85]
	v_pk_mul_f32 v[40:41], v[40:41], v[66:67]
	v_pk_mul_f32 v[34:35], v[34:35], v[88:89]
	v_pk_mul_f32 v[36:37], v[36:37], v[68:69]
	v_pk_mul_f32 v[40:41], v[40:41], v[78:79] op_sel_hi:[1,0]
	v_pk_mul_f32 v[38:39], v[38:39], v[78:79] op_sel_hi:[1,0]
	v_pk_mul_f32 v[36:37], v[36:37], v[78:79] op_sel_hi:[1,0]
	v_pk_mul_f32 v[34:35], v[34:35], v[78:79] op_sel_hi:[1,0]
	v_cvt_pk_bf16_f32 v68, v34, v35
	v_lshlrev_b64 v[34:35], 12, v[86:87]
	v_lshl_add_u64 v[42:43], v[150:151], 0, v[34:35]
	v_cvt_pk_bf16_f32 v66, v38, v39
	v_cvt_pk_bf16_f32 v67, v40, v41
	v_cvt_pk_bf16_f32 v69, v36, v37
	s_waitcnt vmcnt(4)
	v_mov_b32_e32 v46, v226
	v_mov_b32_e32 v47, v227
	v_mov_b32_e32 v48, v228
	v_mov_b32_e32 v49, v229
	v_mov_b32_e32 v54, v230
	v_mov_b32_e32 v55, v231
	v_mov_b32_e32 v56, v232
	v_mov_b32_e32 v57, v233
	v_mov_b32_e32 v70, v242
	v_mov_b32_e32 v71, v243
	v_mov_b32_e32 v72, v244
	v_mov_b32_e32 v73, v245
	v_mov_b32_e32 v78, v246
	v_mov_b32_e32 v79, v247
	v_mov_b32_e32 v80, v248
	v_mov_b32_e32 v81, v249
	v_mov_b32_e32 v38, v234
	v_mov_b32_e32 v39, v235
	v_mov_b32_e32 v40, v236
	v_mov_b32_e32 v41, v237
	v_mov_b32_e32 v34, v238
	v_mov_b32_e32 v35, v239
	v_mov_b32_e32 v36, v240
	v_mov_b32_e32 v37, v241
	s_nop 0
	global_store_dwordx4 v[74:75], v[58:61], off nt
	global_store_dwordx4 v[74:75], v[50:53], off offset:256 nt
	global_store_dwordx4 v[76:77], v[62:65], off nt
	global_store_dwordx4 v[76:77], v[66:69], off offset:256 nt
	s_waitcnt vmcnt(8)
	v_mov_b32_e32 v52, v47
	v_mov_b32_e32 v53, v48
	v_mov_b32_e32 v47, v49
	v_mov_b32_e32 v44, v55
	v_mov_b32_e32 v45, v56
	v_mov_b32_e32 v55, v57
	v_pk_add_f32 v[46:47], v[52:53], v[46:47]
	v_pk_add_f32 v[44:45], v[44:45], v[54:55]
	v_pk_add_f32 v[46:47], v[46:47], v[46:47] op_sel:[0,1] op_sel_hi:[1,0]
	v_pk_add_f32 v[44:45], v[44:45], v[44:45] op_sel:[0,1] op_sel_hi:[1,0]
	v_mul_f32_e32 v47, 0xbfb8aa3b, v30
	v_mov_b32_e32 v45, v44
	v_exp_f32_e32 v47, v47
	s_nop 0
	v_permlane16_swap_b32_e32 v44, v45
	v_add_f32_e32 v44, v44, v45
	v_mov_b32_e32 v45, v46
	s_nop 1
	v_permlane16_swap_b32_e32 v46, v45
	v_add_f32_e32 v45, v46, v45
	v_add_f32_e32 v46, 1.0, v47
	v_mul_f32_e32 v47, 0xbfb8aa3b, v31
	v_exp_f32_e32 v47, v47
	v_rcp_f32_e32 v46, v46
	v_mul_f32_e32 v53, 0xbfb8aa3b, v27
	v_exp_f32_e32 v53, v53
	v_add_f32_e32 v47, 1.0, v47
	v_rcp_f32_e32 v47, v47
	v_mul_f32_e32 v54, 0xbfb8aa3b, v28
	v_mul_f32_e32 v55, 0xbfb8aa3b, v29
	v_exp_f32_e32 v54, v54
	v_pk_mul_f32 v[30:31], v[30:31], v[46:47]
	v_mul_f32_e32 v47, 0xbfb8aa3b, v26
	v_exp_f32_e32 v52, v47
	v_exp_f32_e32 v55, v55
	v_add_f32_e32 v53, 1.0, v53
	v_add_f32_e32 v54, 1.0, v54
	v_add_f32_e32 v52, 1.0, v52
	v_rcp_f32_e32 v52, v52
	v_add_f32_e32 v55, 1.0, v55
	v_rcp_f32_e32 v53, v53
	v_rcp_f32_e32 v54, v54
	v_rcp_f32_e32 v55, v55
	v_lshlrev_b32_e32 v46, 16, v70
	v_and_b32_e32 v47, 0xffff0000, v70
	v_pk_mul_f32 v[30:31], v[30:31], v[46:47]
	v_pk_mul_f32 v[26:27], v[26:27], v[52:53]
	v_mul_f32_e32 v47, 0xbfb8aa3b, v22
	v_mul_f32_e32 v53, 0xbfb8aa3b, v23
	v_pk_mul_f32 v[28:29], v[28:29], v[54:55]
	v_exp_f32_e32 v52, v47
	v_exp_f32_e32 v53, v53
	v_mul_f32_e32 v54, 0xbfb8aa3b, v24
	v_mul_f32_e32 v55, 0xbfb8aa3b, v25
	v_mul_f32_e32 v48, 0xbfb8aa3b, v32
	v_mul_f32_e32 v49, 0xbfb8aa3b, v33
	v_exp_f32_e32 v54, v54
	v_exp_f32_e32 v55, v55
	v_exp_f32_e32 v48, v48
	v_exp_f32_e32 v49, v49
	v_add_f32_e32 v52, 1.0, v52
	v_add_f32_e32 v53, 1.0, v53
	v_rcp_f32_e32 v52, v52
	v_add_f32_e32 v54, 1.0, v54
	v_add_f32_e32 v55, 1.0, v55
	v_rcp_f32_e32 v53, v53
	v_add_f32_e32 v48, 1.0, v48
	v_add_f32_e32 v49, 1.0, v49
	v_rcp_f32_e32 v54, v54
	v_rcp_f32_e32 v55, v55
	v_rcp_f32_e32 v48, v48
	v_rcp_f32_e32 v49, v49
	v_lshlrev_b32_e32 v46, 16, v72
	v_and_b32_e32 v47, 0xffff0000, v72
	v_pk_mul_f32 v[26:27], v[26:27], v[46:47]
	v_pk_mul_f32 v[22:23], v[22:23], v[52:53]
	v_mul_f32_e32 v47, 0xbfb8aa3b, v18
	v_mul_f32_e32 v53, 0xbfb8aa3b, v19
	v_mov_b32_e32 v50, v44
	v_mov_b32_e32 v51, v45
	v_pk_mul_f32 v[24:25], v[24:25], v[54:55]
	v_exp_f32_e32 v52, v47
	v_exp_f32_e32 v53, v53
	v_mul_f32_e32 v54, 0xbfb8aa3b, v20
	v_mul_f32_e32 v55, 0xbfb8aa3b, v21
	v_permlane32_swap_b32_e32 v44, v50
	v_permlane32_swap_b32_e32 v45, v51
	v_pk_mul_f32 v[32:33], v[32:33], v[48:49]
	v_lshlrev_b32_e32 v48, 16, v71
	v_and_b32_e32 v49, 0xffff0000, v71
	v_exp_f32_e32 v54, v54
	v_exp_f32_e32 v55, v55
	v_pk_mul_f32 v[32:33], v[32:33], v[48:49]
	v_lshlrev_b32_e32 v48, 16, v73
	v_and_b32_e32 v49, 0xffff0000, v73
	v_pk_add_f32 v[44:45], v[44:45], v[50:51]
	v_pk_mul_f32 v[28:29], v[28:29], v[48:49]
	v_lshlrev_b32_e32 v48, 16, v79
	v_and_b32_e32 v49, 0xffff0000, v79
	v_pk_fma_f32 v[44:45], v[44:45], s[36:37], v[148:149] op_sel_hi:[1,0,0]
	v_add_f32_e32 v52, 1.0, v52
	v_add_f32_e32 v53, 1.0, v53
	v_pk_mul_f32 v[24:25], v[24:25], v[48:49]
	v_mul_f32_e32 v49, 0x4b800000, v45
	v_cmp_gt_f32_e32 vcc, s76, v45
	v_rcp_f32_e32 v52, v52
	v_add_f32_e32 v54, 1.0, v54
	v_add_f32_e32 v55, 1.0, v55
	v_rcp_f32_e32 v53, v53
	v_cndmask_b32_e32 v45, v45, v49, vcc
	v_rcp_f32_e32 v54, v54
	v_rcp_f32_e32 v55, v55
	v_rsq_f32_e32 v45, v45
	v_lshlrev_b32_e32 v46, 16, v78
	v_and_b32_e32 v47, 0xffff0000, v78
	v_pk_mul_f32 v[22:23], v[22:23], v[46:47]
	v_pk_mul_f32 v[18:19], v[18:19], v[52:53]
	v_lshlrev_b32_e32 v46, 16, v80
	v_and_b32_e32 v47, 0xffff0000, v80
	v_pk_mul_f32 v[20:21], v[20:21], v[54:55]
	v_lshlrev_b32_e32 v48, 16, v81
	v_and_b32_e32 v49, 0xffff0000, v81
	v_pk_mul_f32 v[46:47], v[18:19], v[46:47]
	v_mul_f32_e32 v18, 0x45800000, v45
	v_pk_mul_f32 v[20:21], v[20:21], v[48:49]
	v_cndmask_b32_e32 v48, v45, v18, vcc
	v_pk_mul_f32 v[18:19], v[32:33], v[48:49] op_sel_hi:[1,0]
	v_cmp_gt_f32_e32 vcc, s76, v44
	v_cvt_pk_bf16_f32 v131, v18, v19
	v_pk_mul_f32 v[18:19], v[28:29], v[48:49] op_sel_hi:[1,0]
	v_pk_mul_f32 v[26:27], v[26:27], v[48:49] op_sel_hi:[1,0]
	v_cvt_pk_bf16_f32 v133, v18, v19
	v_pk_mul_f32 v[18:19], v[22:23], v[48:49] op_sel_hi:[1,0]
	v_pk_mul_f32 v[22:23], v[20:21], v[48:49] op_sel_hi:[1,0]
	v_pk_mul_f32 v[20:21], v[46:47], v[48:49] op_sel_hi:[1,0]
	v_cvt_pk_bf16_f32 v132, v26, v27
	v_cvt_pk_bf16_f32 v20, v20, v21
	v_cvt_pk_bf16_f32 v21, v22, v23
	v_mul_f32_e32 v23, 0xbfb8aa3b, v14
	v_exp_f32_e32 v23, v23
	v_mul_f32_e32 v22, 0x4b800000, v44
	v_cndmask_b32_e32 v22, v44, v22, vcc
	v_rsq_f32_e32 v26, v22
	v_add_f32_e32 v22, 1.0, v23
	v_mul_f32_e32 v23, 0xbfb8aa3b, v15
	v_exp_f32_e32 v23, v23
	v_pk_mul_f32 v[24:25], v[24:25], v[48:49] op_sel_hi:[1,0]
	v_cvt_pk_bf16_f32 v18, v18, v19
	v_cvt_pk_bf16_f32 v19, v24, v25
	v_add_f32_e32 v23, 1.0, v23
	v_rcp_f32_e32 v22, v22
	v_mul_f32_e32 v24, 0xbfb8aa3b, v16
	v_mul_f32_e32 v25, 0xbfb8aa3b, v17
	v_rcp_f32_e32 v23, v23
	v_exp_f32_e32 v24, v24
	v_exp_f32_e32 v25, v25
	v_mul_f32_e32 v27, 0x45800000, v26
	v_pk_mul_f32 v[14:15], v[14:15], v[22:23]
	v_lshlrev_b32_e32 v22, 16, v38
	v_and_b32_e32 v23, 0xffff0000, v38
	v_add_f32_e32 v24, 1.0, v24
	v_add_f32_e32 v25, 1.0, v25
	v_pk_mul_f32 v[14:15], v[14:15], v[22:23]
	v_mul_f32_e32 v22, 0xbfb8aa3b, v10
	v_mul_f32_e32 v23, 0xbfb8aa3b, v11
	v_rcp_f32_e32 v24, v24
	v_rcp_f32_e32 v25, v25
	v_exp_f32_e32 v22, v22
	v_exp_f32_e32 v23, v23
	v_cndmask_b32_e32 v26, v26, v27, vcc
	v_pk_mul_f32 v[16:17], v[16:17], v[24:25]
	v_lshlrev_b32_e32 v24, 16, v39
	v_and_b32_e32 v25, 0xffff0000, v39
	v_add_f32_e32 v22, 1.0, v22
	v_add_f32_e32 v23, 1.0, v23
	v_pk_mul_f32 v[16:17], v[16:17], v[24:25]
	v_rcp_f32_e32 v22, v22
	v_mul_f32_e32 v24, 0xbfb8aa3b, v12
	v_mul_f32_e32 v25, 0xbfb8aa3b, v13
	v_rcp_f32_e32 v23, v23
	v_exp_f32_e32 v24, v24
	v_exp_f32_e32 v25, v25
	v_pk_mul_f32 v[16:17], v[16:17], v[26:27] op_sel_hi:[1,0]
	v_pk_mul_f32 v[14:15], v[14:15], v[26:27] op_sel_hi:[1,0]
	v_pk_mul_f32 v[10:11], v[10:11], v[22:23]
	v_cvt_pk_bf16_f32 v14, v14, v15
	v_cvt_pk_bf16_f32 v15, v16, v17
	v_lshlrev_b32_e32 v16, 16, v40
	v_and_b32_e32 v17, 0xffff0000, v40
	v_add_f32_e32 v24, 1.0, v24
	v_add_f32_e32 v25, 1.0, v25
	v_pk_mul_f32 v[10:11], v[10:11], v[16:17]
	v_mul_f32_e32 v16, 0xbfb8aa3b, v6
	v_rcp_f32_e32 v24, v24
	v_rcp_f32_e32 v25, v25
	v_exp_f32_e32 v16, v16
	v_lshlrev_b32_e32 v22, 16, v41
	v_and_b32_e32 v23, 0xffff0000, v41
	v_pk_mul_f32 v[12:13], v[12:13], v[24:25]
	v_add_f32_e32 v16, 1.0, v16
	v_mul_f32_e32 v17, 0xbfb8aa3b, v8
	v_pk_mul_f32 v[12:13], v[12:13], v[22:23]
	v_rcp_f32_e32 v22, v16
	v_mul_f32_e32 v16, 0xbfb8aa3b, v7
	v_exp_f32_e32 v17, v17
	v_mul_f32_e32 v23, 0xbfb8aa3b, v9
	v_exp_f32_e32 v16, v16
	v_exp_f32_e32 v23, v23
	v_add_f32_e32 v17, 1.0, v17
	v_rcp_f32_e32 v24, v17
	v_add_f32_e32 v16, 1.0, v16
	v_add_f32_e32 v17, 1.0, v23
	v_rcp_f32_e32 v25, v17
	v_rcp_f32_e32 v23, v16
	v_pk_mul_f32 v[12:13], v[12:13], v[26:27] op_sel_hi:[1,0]
	v_pk_mul_f32 v[10:11], v[10:11], v[26:27] op_sel_hi:[1,0]
	v_cvt_pk_bf16_f32 v17, v12, v13
	v_cvt_pk_bf16_f32 v16, v10, v11
	v_pk_mul_f32 v[8:9], v[8:9], v[24:25]
	v_pk_mul_f32 v[6:7], v[6:7], v[22:23]
	v_lshlrev_b32_e32 v10, 16, v34
	v_and_b32_e32 v11, 0xffff0000, v34
	v_lshlrev_b32_e32 v12, 16, v35
	v_and_b32_e32 v13, 0xffff0000, v35
	v_pk_mul_f32 v[6:7], v[6:7], v[10:11]
	v_mul_f32_e32 v10, 0xbfb8aa3b, v2
	v_pk_mul_f32 v[8:9], v[8:9], v[12:13]
	v_mul_f32_e32 v11, 0xbfb8aa3b, v3
	v_mul_f32_e32 v12, 0xbfb8aa3b, v4
	v_mul_f32_e32 v13, 0xbfb8aa3b, v5
	v_exp_f32_e32 v10, v10
	v_exp_f32_e32 v11, v11
	v_exp_f32_e32 v12, v12
	v_exp_f32_e32 v13, v13
	v_add_f32_e32 v10, 1.0, v10
	v_add_f32_e32 v11, 1.0, v11
	v_add_f32_e32 v12, 1.0, v12
	v_add_f32_e32 v13, 1.0, v13
	v_rcp_f32_e32 v10, v10
	v_rcp_f32_e32 v12, v12
	v_rcp_f32_e32 v13, v13
	v_rcp_f32_e32 v11, v11
	v_pk_mul_f32 v[8:9], v[8:9], v[26:27] op_sel_hi:[1,0]
	v_pk_mul_f32 v[6:7], v[6:7], v[26:27] op_sel_hi:[1,0]
	v_pk_mul_f32 v[4:5], v[4:5], v[12:13]
	v_cvt_pk_bf16_f32 v6, v6, v7
	v_cvt_pk_bf16_f32 v7, v8, v9
	v_pk_mul_f32 v[2:3], v[2:3], v[10:11]
	v_lshlrev_b32_e32 v8, 16, v36
	v_and_b32_e32 v9, 0xffff0000, v36
	v_lshlrev_b32_e32 v10, 16, v37
	v_and_b32_e32 v11, 0xffff0000, v37
	v_pk_mul_f32 v[2:3], v[2:3], v[8:9]
	v_pk_mul_f32 v[4:5], v[4:5], v[10:11]
	v_pk_mul_f32 v[30:31], v[30:31], v[48:49] op_sel_hi:[1,0]
	v_pk_mul_f32 v[4:5], v[4:5], v[26:27] op_sel_hi:[1,0]
	v_pk_mul_f32 v[2:3], v[2:3], v[26:27] op_sel_hi:[1,0]
	v_cvt_pk_bf16_f32 v130, v30, v31
	v_cvt_pk_bf16_f32 v8, v2, v3
	v_cvt_pk_bf16_f32 v9, v4, v5
	global_store_dwordx4 v[42:43], v[6:9], off nt
	global_store_dwordx4 v[42:43], v[14:17], off offset:256 nt
	global_store_dwordx4 v[152:153], v[18:21], off nt
	s_andn2_b64 vcc, exec, s[2:3]
	s_mov_b64 s[0:1], -1
	global_store_dwordx4 v[152:153], v[130:133], off offset:256 nt
	s_cbranch_vccnz .LBB0_678
